# nt hint on the final f32 output stores
# speedup vs baseline: 1.0703x; 1.0021x over previous
;     __device__ __forceinline__ void operator()(const f32x4 (&acc)[2][2][4][2], const Unit& u, int wr, int wc, int fr, int fq, const LAS float* rsl) const {
;     ...
;         for (int bj = 0; bj < 2; ++bj) { const size_t off = (size_t)row0 * 1024 + col0 + bj * 128; xr[0][bj] = *(const u32x4*)(x1b + off); pr[0][bj] = *(const u32x4*)(pp + off); }
; #pragma unroll
;         for (int ai = 0; ai < 2; ++ai)
; #pragma unroll
;             for (int m = 0; m < 4; ++m) { const int row = row0 + ai * 128 + m * 16; float s = 0.f; const int bt = ai * 4 + m;
;                 if (bt < 7) { const int nrow = row0 + ((bt + 1) >> 2) * 128 + ((bt + 1) & 3) * 16;
; #pragma unroll
;                     for (int bj = 0; bj < 2; ++bj) { const size_t off = (size_t)nrow * 1024 + col0 + bj * 128; xr[(bt + 1) & 1][bj] = *(const u32x4*)(x1b + off); pr[(bt + 1) & 1][bj] = *(const u32x4*)(pp + off); } }
; #pragma unroll
;                 for (int bj = 0; bj < 2; ++bj) { const size_t off = (size_t)row * 1024 + col0 + bj * 128;
;                     float xv[8], pv[8]; unpack8(xr[bt & 1][bj], xv); unpack8(pr[bt & 1][bj], pv);
;                     f32x4 x0 = (f32x4){xv[0], xv[1], xv[2], xv[3]}, x1 = (f32x4){xv[4], xv[5], xv[6], xv[7]};
;                     const f32x4 g0 = acc[ai][bj][m][0], g1 = acc[ai][bj][m][1];
; #pragma unroll
;                     for (int j = 0; j < 4; ++j) { float sa, sb; sigmoid2(g0[j], g1[j], sa, sb); x0[j] += sa * pv[j]; x1[j] += sb * pv[4 + j]; s += x0[j] * x0[j] + x1[j] * x1[j]; }
;                     if (xb) store8bf(xb + off, x0, x1);
;                     else { *(f32x4*)(X + off) = x0; *(f32x4*)(X + off + 4) = x1; } }
.LBB0_119:
	s_cmp_lt_i32 s1, 2
	s_mov_b64 s[36:37], -1
	s_cbranch_scc1 .LBB0_237
	s_cmp_gt_i32 s1, 2
	s_cbranch_scc0 .LBB0_218
	v_add_u32_e32 v192, s34, v171
	v_lshl_or_b32 v190, s48, 8, v227
	v_ashrrev_i32_e32 v193, 31, v192
	v_lshlrev_b64 v[128:129], 10, v[192:193]
	v_ashrrev_i32_e32 v191, 31, v190
	v_lshl_add_u64 v[166:167], v[128:129], 0, v[190:191]
	v_lshlrev_b64 v[128:129], 1, v[166:167]
	v_lshl_add_u64 v[130:131], s[98:99], 0, v[128:129]
	v_lshl_add_u64 v[128:129], s[64:65], 0, v[128:129]
	global_load_dwordx4 v[158:161], v[130:131], off
	global_load_dwordx4 v[162:165], v[128:129], off
	v_or_b32_e32 v200, 0x80, v166
	v_mov_b32_e32 v201, v167
	v_lshlrev_b64 v[128:129], 1, v[200:201]
	v_or_b32_e32 v194, 16, v192
	v_lshl_add_u64 v[130:131], s[98:99], 0, v[128:129]
	v_lshl_add_u64 v[128:129], s[64:65], 0, v[128:129]
	v_ashrrev_i32_e32 v195, 31, v194
	global_load_dwordx4 v[144:147], v[130:131], off
	global_load_dwordx4 v[148:151], v[128:129], off
	v_lshlrev_b64 v[128:129], 10, v[194:195]
	v_lshl_add_u64 v[198:199], v[128:129], 0, v[190:191]
	v_lshlrev_b64 v[128:129], 1, v[198:199]
	v_or_b32_e32 v196, 0x80, v198
	v_mov_b32_e32 v197, v199
	v_lshl_add_u64 v[130:131], s[98:99], 0, v[128:129]
	v_lshl_add_u64 v[128:129], s[64:65], 0, v[128:129]
	v_lshlrev_b64 v[132:133], 1, v[196:197]
	global_load_dwordx4 v[136:139], v[130:131], off
	global_load_dwordx4 v[140:143], v[128:129], off
	v_lshl_add_u64 v[128:129], s[98:99], 0, v[132:133]
	v_lshl_add_u64 v[132:133], s[64:65], 0, v[132:133]
	global_load_dwordx4 v[128:131], v[128:129], off
	v_max_f32_e64 v153, -v120, -v120
	global_load_dwordx4 v[132:135], v[132:133], off
	v_min_f32_e32 v153, 0x42200000, v153
	v_mul_f32_e32 v153, 0x3fb8aa3b, v153
	v_max_f32_e64 v152, -v124, -v124
	v_exp_f32_e32 v154, v153
	v_max_f32_e64 v153, -v125, -v125
	v_max_f32_e64 v155, -v121, -v121
	v_min_f32_e32 v152, 0x42200000, v152
	v_min_f32_e32 v153, 0x42200000, v153
	v_min_f32_e32 v155, 0x42200000, v155
	v_mul_f32_e32 v152, 0x3fb8aa3b, v152
	v_mul_f32_e32 v153, 0x3fb8aa3b, v153
	v_mul_f32_e32 v155, 0x3fb8aa3b, v155
	v_exp_f32_e32 v152, v152
	v_exp_f32_e32 v153, v153
	v_exp_f32_e32 v155, v155
	s_and_b64 vcc, exec, s[96:97]
	v_pk_add_f32 v[230:231], v[152:153], 1.0 op_sel_hi:[1,0]
	v_pk_add_f32 v[154:155], v[154:155], 1.0 op_sel_hi:[1,0]
	s_waitcnt vmcnt(0)
	v_lshlrev_b32_e32 v156, 16, v158
	v_pk_mul_f32 v[152:153], v[230:231], v[154:155]
	v_and_b32_e32 v157, 0xffff0000, v158
	v_rcp_f32_e32 v232, v152
	v_rcp_f32_e32 v233, v153
	v_lshlrev_b32_e32 v202, 16, v162
	v_and_b32_e32 v203, 0xffff0000, v162
	v_lshlrev_b32_e32 v204, 16, v160
	v_and_b32_e32 v205, 0xffff0000, v160
	v_lshlrev_b32_e32 v206, 16, v164
	v_and_b32_e32 v207, 0xffff0000, v164
	v_pk_mul_f32 v[152:153], v[154:155], v[232:233]
	v_pk_mul_f32 v[154:155], v[230:231], v[232:233]
	v_pk_fma_f32 v[152:153], v[152:153], v[202:203], v[156:157]
	v_pk_fma_f32 v[156:157], v[154:155], v[206:207], v[204:205]
	v_max_f32_e64 v155, -v122, -v122
	v_min_f32_e32 v155, 0x42200000, v155
	v_mul_f32_e32 v155, 0x3fb8aa3b, v155
	v_max_f32_e64 v154, -v126, -v126
	v_exp_f32_e32 v202, v155
	v_max_f32_e64 v155, -v127, -v127
	v_max_f32_e64 v158, -v123, -v123
	v_min_f32_e32 v154, 0x42200000, v154
	v_min_f32_e32 v155, 0x42200000, v155
	v_min_f32_e32 v158, 0x42200000, v158
	v_mul_f32_e32 v154, 0x3fb8aa3b, v154
	v_mul_f32_e32 v155, 0x3fb8aa3b, v155
	v_mul_f32_e32 v158, 0x3fb8aa3b, v158
	v_exp_f32_e32 v154, v154
	v_exp_f32_e32 v155, v155
	v_exp_f32_e32 v203, v158
	v_lshlrev_b32_e32 v158, 16, v159
	v_and_b32_e32 v159, 0xffff0000, v159
	v_pk_add_f32 v[204:205], v[154:155], 1.0 op_sel_hi:[1,0]
	v_pk_add_f32 v[202:203], v[202:203], 1.0 op_sel_hi:[1,0]
	v_lshlrev_b32_e32 v162, 16, v163
	v_pk_mul_f32 v[154:155], v[204:205], v[202:203]
	v_and_b32_e32 v163, 0xffff0000, v163
	v_rcp_f32_e32 v206, v154
	v_rcp_f32_e32 v207, v155
	v_lshlrev_b32_e32 v160, 16, v161
	v_and_b32_e32 v161, 0xffff0000, v161
	v_lshlrev_b32_e32 v164, 16, v165
	v_pk_mul_f32 v[154:155], v[202:203], v[206:207]
	v_and_b32_e32 v165, 0xffff0000, v165
	v_pk_fma_f32 v[154:155], v[154:155], v[162:163], v[158:159]
	v_pk_mul_f32 v[158:159], v[204:205], v[206:207]
	v_lshl_add_u64 v[202:203], v[166:167], 2, s[8:9]
	v_pk_fma_f32 v[158:159], v[158:159], v[164:165], v[160:161]
	s_cbranch_vccz .LBB0_123
	global_store_dwordx4 v[202:203], v[152:155], off nt
	global_store_dwordx4 v[202:203], v[156:159], off offset:16 nt
	s_mov_b64 s[36:37], 0

;     __device__ __forceinline__ void operator()(const f32x4 (&acc)[2][2][4][2], const Unit& u, int wr, int wc, int fr, int fq, const LAS float* rsl) const {
;     ...
;                     for (int j = 0; j < 4; ++j) { float sa, sb; sigmoid2(g0[j], g1[j], sa, sb); x0[j] += sa * pv[j]; x1[j] += sb * pv[4 + j]; s += x0[j] * x0[j] + x1[j] * x1[j]; }
;                     if (xb) store8bf(xb + off, x0, x1);
;                     else { *(f32x4*)(X + off) = x0; *(f32x4*)(X + off + 4) = x1; } }
.LBB0_128:
	global_store_dwordx4 v[202:203], v[160:163], off offset:512 nt
	global_store_dwordx4 v[202:203], v[164:167], off offset:528 nt
	s_cbranch_execnz .LBB0_127

;     __device__ __forceinline__ void operator()(const f32x4 (&acc)[2][2][4][2], const Unit& u, int wr, int wc, int fr, int fq, const LAS float* rsl) const {
;     ...
;             for (int m = 0; m < 4; ++m) { const int row = row0 + ai * 128 + m * 16; float s = 0.f; const int bt = ai * 4 + m;
;                 if (bt < 7) { const int nrow = row0 + ((bt + 1) >> 2) * 128 + ((bt + 1) & 3) * 16;
; #pragma unroll
;                     for (int bj = 0; bj < 2; ++bj) { const size_t off = (size_t)nrow * 1024 + col0 + bj * 128; xr[(bt + 1) & 1][bj] = *(const u32x4*)(x1b + off); pr[(bt + 1) & 1][bj] = *(const u32x4*)(pp + off); } }
; #pragma unroll
;                 for (int bj = 0; bj < 2; ++bj) { const size_t off = (size_t)row * 1024 + col0 + bj * 128;
;                     float xv[8], pv[8]; unpack8(xr[bt & 1][bj], xv); unpack8(pr[bt & 1][bj], pv);
;                     f32x4 x0 = (f32x4){xv[0], xv[1], xv[2], xv[3]}, x1 = (f32x4){xv[4], xv[5], xv[6], xv[7]};
;                     const f32x4 g0 = acc[ai][bj][m][0], g1 = acc[ai][bj][m][1];
; #pragma unroll
;                     for (int j = 0; j < 4; ++j) { float sa, sb; sigmoid2(g0[j], g1[j], sa, sb); x0[j] += sa * pv[j]; x1[j] += sb * pv[4 + j]; s += x0[j] * x0[j] + x1[j] * x1[j]; }
;                     if (xb) store8bf(xb + off, x0, x1);
;                     else { *(f32x4*)(X + off) = x0; *(f32x4*)(X + off + 4) = x1; } }
.LBB0_133:
	v_or_b32_e32 v200, 32, v192
	v_ashrrev_i32_e32 v201, 31, v200
	s_waitcnt lgkmcnt(0)
	v_lshlrev_b64 v[144:145], 10, v[200:201]
	v_lshl_add_u64 v[204:205], v[144:145], 0, v[190:191]
	v_lshlrev_b64 v[144:145], 1, v[204:205]
	v_or_b32_e32 v202, 0x80, v204
	v_mov_b32_e32 v203, v205
	v_lshl_add_u64 v[146:147], s[98:99], 0, v[144:145]
	v_lshl_add_u64 v[144:145], s[64:65], 0, v[144:145]
	v_lshlrev_b64 v[148:149], 1, v[202:203]
	global_load_dwordx4 v[152:155], v[146:147], off
	global_load_dwordx4 v[156:159], v[144:145], off
	v_lshl_add_u64 v[144:145], s[98:99], 0, v[148:149]
	v_lshl_add_u64 v[148:149], s[64:65], 0, v[148:149]
	global_load_dwordx4 v[144:147], v[144:145], off
	v_max_f32_e64 v161, -v104, -v104
	global_load_dwordx4 v[148:151], v[148:149], off
	v_min_f32_e32 v161, 0x42200000, v161
	v_mul_f32_e32 v161, 0x3fb8aa3b, v161
	v_max_f32_e64 v160, -v112, -v112
	v_exp_f32_e32 v162, v161
	v_max_f32_e64 v161, -v113, -v113
	v_max_f32_e64 v163, -v105, -v105
	v_min_f32_e32 v160, 0x42200000, v160
	v_min_f32_e32 v161, 0x42200000, v161
	v_min_f32_e32 v163, 0x42200000, v163
	v_mul_f32_e32 v160, 0x3fb8aa3b, v160
	v_mul_f32_e32 v161, 0x3fb8aa3b, v161
	v_mul_f32_e32 v163, 0x3fb8aa3b, v163
	v_exp_f32_e32 v160, v160
	v_exp_f32_e32 v161, v161
	v_exp_f32_e32 v163, v163
	v_lshlrev_b32_e32 v164, 16, v136
	v_and_b32_e32 v165, 0xffff0000, v136
	v_pk_add_f32 v[232:233], v[160:161], 1.0 op_sel_hi:[1,0]
	v_pk_add_f32 v[162:163], v[162:163], 1.0 op_sel_hi:[1,0]
	v_max_f32_e64 v136, -v114, -v114
	v_pk_mul_f32 v[160:161], v[232:233], v[162:163]
	v_min_f32_e32 v136, 0x42200000, v136
	v_rcp_f32_e32 v234, v160
	v_rcp_f32_e32 v235, v161
	v_lshlrev_b32_e32 v166, 16, v140
	v_and_b32_e32 v167, 0xffff0000, v140
	v_lshlrev_b32_e32 v206, 16, v138
	v_and_b32_e32 v207, 0xffff0000, v138
	v_lshlrev_b32_e32 v230, 16, v142
	v_and_b32_e32 v231, 0xffff0000, v142
	v_pk_mul_f32 v[160:161], v[162:163], v[234:235]
	v_pk_mul_f32 v[162:163], v[232:233], v[234:235]
	v_mul_f32_e32 v136, 0x3fb8aa3b, v136
	v_pk_fma_f32 v[160:161], v[160:161], v[166:167], v[164:165]
	v_pk_fma_f32 v[164:165], v[162:163], v[230:231], v[206:207]
	v_exp_f32_e32 v162, v136
	v_max_f32_e64 v136, -v106, -v106
	v_min_f32_e32 v136, 0x42200000, v136
	v_mul_f32_e32 v136, 0x3fb8aa3b, v136
	v_exp_f32_e32 v166, v136
	v_max_f32_e64 v136, -v115, -v115
	v_min_f32_e32 v136, 0x42200000, v136
	v_mul_f32_e32 v136, 0x3fb8aa3b, v136
	v_exp_f32_e32 v163, v136
	v_max_f32_e64 v136, -v107, -v107
	v_min_f32_e32 v136, 0x42200000, v136
	v_mul_f32_e32 v136, 0x3fb8aa3b, v136
	v_exp_f32_e32 v167, v136
	v_pk_add_f32 v[206:207], v[162:163], 1.0 op_sel_hi:[1,0]
	v_lshlrev_b32_e32 v136, 16, v137
	v_and_b32_e32 v137, 0xffff0000, v137
	v_pk_add_f32 v[166:167], v[166:167], 1.0 op_sel_hi:[1,0]
	v_lshlrev_b32_e32 v140, 16, v141
	v_pk_mul_f32 v[162:163], v[206:207], v[166:167]
	v_and_b32_e32 v141, 0xffff0000, v141
	v_rcp_f32_e32 v230, v162
	v_rcp_f32_e32 v231, v163
	v_lshlrev_b32_e32 v138, 16, v139
	v_and_b32_e32 v139, 0xffff0000, v139
	v_lshlrev_b32_e32 v142, 16, v143
	v_pk_mul_f32 v[162:163], v[166:167], v[230:231]
	v_and_b32_e32 v143, 0xffff0000, v143
	v_pk_fma_f32 v[162:163], v[162:163], v[140:141], v[136:137]
	v_pk_mul_f32 v[136:137], v[206:207], v[230:231]
	s_mov_b64 s[36:37], -1
	v_pk_fma_f32 v[166:167], v[136:137], v[142:143], v[138:139]
	s_and_b64 vcc, exec, s[96:97]
	v_lshl_add_u64 v[206:207], v[198:199], 2, s[8:9]
	s_cbranch_vccz .LBB0_135
	global_store_dwordx4 v[206:207], v[160:163], off nt
	global_store_dwordx4 v[206:207], v[164:167], off offset:16 nt
	s_mov_b64 s[36:37], 0

;     __device__ __forceinline__ void operator()(const f32x4 (&acc)[2][2][4][2], const Unit& u, int wr, int wc, int fr, int fq, const LAS float* rsl) const {
;     ...
;                     for (int j = 0; j < 4; ++j) { float sa, sb; sigmoid2(g0[j], g1[j], sa, sb); x0[j] += sa * pv[j]; x1[j] += sb * pv[4 + j]; s += x0[j] * x0[j] + x1[j] * x1[j]; }
;                     if (xb) store8bf(xb + off, x0, x1);
;                     else { *(f32x4*)(X + off) = x0; *(f32x4*)(X + off + 4) = x1; } }
.LBB0_140:
	global_store_dwordx4 v[206:207], v[136:139], off offset:512 nt
	global_store_dwordx4 v[206:207], v[140:143], off offset:528 nt
	s_cbranch_execnz .LBB0_139

;     __device__ __forceinline__ void operator()(const f32x4 (&acc)[2][2][4][2], const Unit& u, int wr, int wc, int fr, int fq, const LAS float* rsl) const {
;     ...
;             for (int m = 0; m < 4; ++m) { const int row = row0 + ai * 128 + m * 16; float s = 0.f; const int bt = ai * 4 + m;
;                 if (bt < 7) { const int nrow = row0 + ((bt + 1) >> 2) * 128 + ((bt + 1) & 3) * 16;
; #pragma unroll
;                     for (int bj = 0; bj < 2; ++bj) { const size_t off = (size_t)nrow * 1024 + col0 + bj * 128; xr[(bt + 1) & 1][bj] = *(const u32x4*)(x1b + off); pr[(bt + 1) & 1][bj] = *(const u32x4*)(pp + off); } }
; #pragma unroll
;                 for (int bj = 0; bj < 2; ++bj) { const size_t off = (size_t)row * 1024 + col0 + bj * 128;
;                     float xv[8], pv[8]; unpack8(xr[bt & 1][bj], xv); unpack8(pr[bt & 1][bj], pv);
;                     f32x4 x0 = (f32x4){xv[0], xv[1], xv[2], xv[3]}, x1 = (f32x4){xv[4], xv[5], xv[6], xv[7]};
;                     const f32x4 g0 = acc[ai][bj][m][0], g1 = acc[ai][bj][m][1];
; #pragma unroll
;                     for (int j = 0; j < 4; ++j) { float sa, sb; sigmoid2(g0[j], g1[j], sa, sb); x0[j] += sa * pv[j]; x1[j] += sb * pv[4 + j]; s += x0[j] * x0[j] + x1[j] * x1[j]; }
;                     if (xb) store8bf(xb + off, x0, x1);
;                     else { *(f32x4*)(X + off) = x0; *(f32x4*)(X + off + 4) = x1; } }
.LBB0_145:
	v_or_b32_e32 v196, 48, v192
	v_ashrrev_i32_e32 v197, 31, v196
	s_waitcnt lgkmcnt(0)
	v_lshlrev_b64 v[128:129], 10, v[196:197]
	v_lshl_add_u64 v[206:207], v[128:129], 0, v[190:191]
	v_lshlrev_b64 v[128:129], 1, v[206:207]
	v_or_b32_e32 v198, 0x80, v206
	v_mov_b32_e32 v199, v207
	v_lshl_add_u64 v[130:131], s[98:99], 0, v[128:129]
	v_lshl_add_u64 v[128:129], s[64:65], 0, v[128:129]
	v_lshlrev_b64 v[132:133], 1, v[198:199]
	global_load_dwordx4 v[140:143], v[130:131], off
	global_load_dwordx4 v[160:163], v[128:129], off
	v_lshl_add_u64 v[128:129], s[98:99], 0, v[132:133]
	v_lshl_add_u64 v[132:133], s[64:65], 0, v[132:133]
	global_load_dwordx4 v[128:131], v[128:129], off
	v_max_f32_e64 v135, -v89, -v89
	global_load_dwordx4 v[136:139], v[132:133], off
	v_max_f32_e64 v133, -v88, -v88
	v_min_f32_e32 v133, 0x42200000, v133
	v_mul_f32_e32 v133, 0x3fb8aa3b, v133
	v_max_f32_e64 v132, -v96, -v96
	v_exp_f32_e32 v134, v133
	v_max_f32_e64 v133, -v97, -v97
	v_min_f32_e32 v132, 0x42200000, v132
	v_min_f32_e32 v133, 0x42200000, v133
	v_min_f32_e32 v135, 0x42200000, v135
	v_mul_f32_e32 v132, 0x3fb8aa3b, v132
	v_mul_f32_e32 v133, 0x3fb8aa3b, v133
	v_mul_f32_e32 v135, 0x3fb8aa3b, v135
	v_exp_f32_e32 v132, v132
	v_exp_f32_e32 v133, v133
	v_exp_f32_e32 v135, v135
	s_waitcnt vmcnt(7)
	v_lshlrev_b32_e32 v164, 16, v152
	v_and_b32_e32 v165, 0xffff0000, v152
	v_pk_add_f32 v[232:233], v[132:133], 1.0 op_sel_hi:[1,0]
	v_pk_add_f32 v[134:135], v[134:135], 1.0 op_sel_hi:[1,0]
	s_waitcnt vmcnt(6)
	v_lshlrev_b32_e32 v166, 16, v156
	v_pk_mul_f32 v[132:133], v[232:233], v[134:135]
	v_and_b32_e32 v167, 0xffff0000, v156
	v_rcp_f32_e32 v234, v132
	v_rcp_f32_e32 v235, v133
	v_lshlrev_b32_e32 v194, 16, v154
	v_and_b32_e32 v195, 0xffff0000, v154
	v_lshlrev_b32_e32 v230, 16, v158
	v_and_b32_e32 v231, 0xffff0000, v158
	v_pk_mul_f32 v[132:133], v[134:135], v[234:235]
	v_pk_mul_f32 v[134:135], v[232:233], v[234:235]
	v_pk_fma_f32 v[132:133], v[132:133], v[166:167], v[164:165]
	v_pk_fma_f32 v[164:165], v[134:135], v[230:231], v[194:195]
	v_max_f32_e64 v135, -v90, -v90
	v_min_f32_e32 v135, 0x42200000, v135
	v_mul_f32_e32 v135, 0x3fb8aa3b, v135
	v_max_f32_e64 v134, -v98, -v98
	v_exp_f32_e32 v166, v135
	v_max_f32_e64 v135, -v99, -v99
	v_max_f32_e64 v152, -v91, -v91
	v_min_f32_e32 v134, 0x42200000, v134
	v_min_f32_e32 v135, 0x42200000, v135
	v_min_f32_e32 v152, 0x42200000, v152
	v_mul_f32_e32 v134, 0x3fb8aa3b, v134
	v_mul_f32_e32 v135, 0x3fb8aa3b, v135
	v_mul_f32_e32 v152, 0x3fb8aa3b, v152
	v_exp_f32_e32 v134, v134
	v_exp_f32_e32 v135, v135
	v_exp_f32_e32 v167, v152
	v_lshlrev_b32_e32 v152, 16, v153
	v_and_b32_e32 v153, 0xffff0000, v153
	v_pk_add_f32 v[194:195], v[134:135], 1.0 op_sel_hi:[1,0]
	v_pk_add_f32 v[166:167], v[166:167], 1.0 op_sel_hi:[1,0]
	v_lshlrev_b32_e32 v156, 16, v157
	v_pk_mul_f32 v[134:135], v[194:195], v[166:167]
	v_and_b32_e32 v157, 0xffff0000, v157
	v_rcp_f32_e32 v230, v134
	v_rcp_f32_e32 v231, v135
	v_lshlrev_b32_e32 v154, 16, v155
	v_and_b32_e32 v155, 0xffff0000, v155
	v_lshlrev_b32_e32 v158, 16, v159
	v_pk_mul_f32 v[134:135], v[166:167], v[230:231]
	v_and_b32_e32 v159, 0xffff0000, v159
	v_pk_fma_f32 v[134:135], v[134:135], v[156:157], v[152:153]
	v_pk_mul_f32 v[152:153], v[194:195], v[230:231]
	s_mov_b64 s[36:37], -1
	v_pk_fma_f32 v[166:167], v[152:153], v[158:159], v[154:155]
	s_and_b64 vcc, exec, s[96:97]
	v_lshl_add_u64 v[194:195], v[204:205], 2, s[8:9]
	s_cbranch_vccz .LBB0_147
	global_store_dwordx4 v[194:195], v[132:135], off nt
	global_store_dwordx4 v[194:195], v[164:167], off offset:16 nt
	s_mov_b64 s[36:37], 0

;     __device__ __forceinline__ void operator()(const f32x4 (&acc)[2][2][4][2], const Unit& u, int wr, int wc, int fr, int fq, const LAS float* rsl) const {
;     ...
;                     for (int j = 0; j < 4; ++j) { float sa, sb; sigmoid2(g0[j], g1[j], sa, sb); x0[j] += sa * pv[j]; x1[j] += sb * pv[4 + j]; s += x0[j] * x0[j] + x1[j] * x1[j]; }
;                     if (xb) store8bf(xb + off, x0, x1);
;                     else { *(f32x4*)(X + off) = x0; *(f32x4*)(X + off + 4) = x1; } }
.LBB0_152:
	global_store_dwordx4 v[194:195], v[152:155], off offset:512 nt
	global_store_dwordx4 v[194:195], v[156:159], off offset:528 nt
	s_cbranch_execnz .LBB0_151

;     __device__ __forceinline__ void operator()(const f32x4 (&acc)[2][2][4][2], const Unit& u, int wr, int wc, int fr, int fq, const LAS float* rsl) const {
;     ...
;             for (int m = 0; m < 4; ++m) { const int row = row0 + ai * 128 + m * 16; float s = 0.f; const int bt = ai * 4 + m;
;                 if (bt < 7) { const int nrow = row0 + ((bt + 1) >> 2) * 128 + ((bt + 1) & 3) * 16;
; #pragma unroll
;                     for (int bj = 0; bj < 2; ++bj) { const size_t off = (size_t)nrow * 1024 + col0 + bj * 128; xr[(bt + 1) & 1][bj] = *(const u32x4*)(x1b + off); pr[(bt + 1) & 1][bj] = *(const u32x4*)(pp + off); } }
; #pragma unroll
;                 for (int bj = 0; bj < 2; ++bj) { const size_t off = (size_t)row * 1024 + col0 + bj * 128;
;                     float xv[8], pv[8]; unpack8(xr[bt & 1][bj], xv); unpack8(pr[bt & 1][bj], pv);
;                     f32x4 x0 = (f32x4){xv[0], xv[1], xv[2], xv[3]}, x1 = (f32x4){xv[4], xv[5], xv[6], xv[7]};
;                     const f32x4 g0 = acc[ai][bj][m][0], g1 = acc[ai][bj][m][1];
; #pragma unroll
;                     for (int j = 0; j < 4; ++j) { float sa, sb; sigmoid2(g0[j], g1[j], sa, sb); x0[j] += sa * pv[j]; x1[j] += sb * pv[4 + j]; s += x0[j] * x0[j] + x1[j] * x1[j]; }
;                     if (xb) store8bf(xb + off, x0, x1);
;                     else { *(f32x4*)(X + off) = x0; *(f32x4*)(X + off + 4) = x1; } }
.LBB0_157:
	v_add_u32_e32 v194, 0x80, v192
	v_ashrrev_i32_e32 v195, 31, v194
	s_waitcnt lgkmcnt(0)
	v_lshlrev_b64 v[132:133], 10, v[194:195]
	v_lshl_add_u64 v[202:203], v[132:133], 0, v[190:191]
	v_lshlrev_b64 v[132:133], 1, v[202:203]
	v_or_b32_e32 v200, 0x80, v202
	v_mov_b32_e32 v201, v203
	v_lshl_add_u64 v[134:135], s[98:99], 0, v[132:133]
	v_lshl_add_u64 v[132:133], s[64:65], 0, v[132:133]
	v_lshlrev_b64 v[144:145], 1, v[200:201]
	global_load_dwordx4 v[148:151], v[134:135], off
	global_load_dwordx4 v[164:167], v[132:133], off
	v_lshl_add_u64 v[132:133], s[98:99], 0, v[144:145]
	v_lshl_add_u64 v[144:145], s[64:65], 0, v[144:145]
	global_load_dwordx4 v[132:135], v[132:133], off
	v_max_f32_e64 v153, -v72, -v72
	global_load_dwordx4 v[144:147], v[144:145], off
	v_min_f32_e32 v153, 0x42200000, v153
	v_mul_f32_e32 v153, 0x3fb8aa3b, v153
	v_max_f32_e64 v152, -v80, -v80
	v_exp_f32_e32 v154, v153
	v_max_f32_e64 v153, -v81, -v81
	v_max_f32_e64 v155, -v73, -v73
	v_min_f32_e32 v152, 0x42200000, v152
	v_min_f32_e32 v153, 0x42200000, v153
	v_min_f32_e32 v155, 0x42200000, v155
	v_mul_f32_e32 v152, 0x3fb8aa3b, v152
	v_mul_f32_e32 v153, 0x3fb8aa3b, v153
	v_mul_f32_e32 v155, 0x3fb8aa3b, v155
	v_exp_f32_e32 v152, v152
	v_exp_f32_e32 v153, v153
	v_exp_f32_e32 v155, v155
	s_waitcnt vmcnt(7)
	v_lshlrev_b32_e32 v156, 16, v140
	v_and_b32_e32 v157, 0xffff0000, v140
	v_pk_add_f32 v[232:233], v[152:153], 1.0 op_sel_hi:[1,0]
	v_pk_add_f32 v[154:155], v[154:155], 1.0 op_sel_hi:[1,0]
	v_max_f32_e64 v140, -v82, -v82
	v_pk_mul_f32 v[152:153], v[232:233], v[154:155]
	v_min_f32_e32 v140, 0x42200000, v140
	v_rcp_f32_e32 v234, v152
	v_rcp_f32_e32 v235, v153
	s_waitcnt vmcnt(6)
	v_lshlrev_b32_e32 v158, 16, v160
	v_and_b32_e32 v159, 0xffff0000, v160
	v_lshlrev_b32_e32 v204, 16, v142
	v_and_b32_e32 v205, 0xffff0000, v142
	v_lshlrev_b32_e32 v230, 16, v162
	v_and_b32_e32 v231, 0xffff0000, v162
	v_pk_mul_f32 v[152:153], v[154:155], v[234:235]
	v_pk_mul_f32 v[154:155], v[232:233], v[234:235]
	v_mul_f32_e32 v140, 0x3fb8aa3b, v140
	v_pk_fma_f32 v[152:153], v[152:153], v[158:159], v[156:157]
	v_pk_fma_f32 v[156:157], v[154:155], v[230:231], v[204:205]
	v_exp_f32_e32 v154, v140
	v_max_f32_e64 v140, -v74, -v74
	v_min_f32_e32 v140, 0x42200000, v140
	v_mul_f32_e32 v140, 0x3fb8aa3b, v140
	v_exp_f32_e32 v158, v140
	v_max_f32_e64 v140, -v83, -v83
	v_min_f32_e32 v140, 0x42200000, v140
	v_mul_f32_e32 v140, 0x3fb8aa3b, v140
	v_exp_f32_e32 v155, v140
	v_max_f32_e64 v140, -v75, -v75
	v_min_f32_e32 v140, 0x42200000, v140
	v_mul_f32_e32 v140, 0x3fb8aa3b, v140
	v_exp_f32_e32 v159, v140
	v_pk_add_f32 v[204:205], v[154:155], 1.0 op_sel_hi:[1,0]
	v_lshlrev_b32_e32 v140, 16, v141
	v_and_b32_e32 v141, 0xffff0000, v141
	v_pk_add_f32 v[158:159], v[158:159], 1.0 op_sel_hi:[1,0]
	v_lshlrev_b32_e32 v160, 16, v161
	v_pk_mul_f32 v[154:155], v[204:205], v[158:159]
	v_and_b32_e32 v161, 0xffff0000, v161
	v_rcp_f32_e32 v230, v154
	v_rcp_f32_e32 v231, v155
	v_lshlrev_b32_e32 v142, 16, v143
	v_and_b32_e32 v143, 0xffff0000, v143
	v_lshlrev_b32_e32 v162, 16, v163
	v_pk_mul_f32 v[154:155], v[158:159], v[230:231]
	v_and_b32_e32 v163, 0xffff0000, v163
	v_pk_fma_f32 v[154:155], v[154:155], v[160:161], v[140:141]
	v_pk_mul_f32 v[140:141], v[204:205], v[230:231]
	s_mov_b64 s[36:37], -1
	v_pk_fma_f32 v[158:159], v[140:141], v[162:163], v[142:143]
	s_and_b64 vcc, exec, s[96:97]
	v_lshl_add_u64 v[204:205], v[206:207], 2, s[8:9]
	s_cbranch_vccz .LBB0_159
	global_store_dwordx4 v[204:205], v[152:155], off nt
	global_store_dwordx4 v[204:205], v[156:159], off offset:16 nt
	s_mov_b64 s[36:37], 0

;     __device__ __forceinline__ void operator()(const f32x4 (&acc)[2][2][4][2], const Unit& u, int wr, int wc, int fr, int fq, const LAS float* rsl) const {
;     ...
;                     for (int j = 0; j < 4; ++j) { float sa, sb; sigmoid2(g0[j], g1[j], sa, sb); x0[j] += sa * pv[j]; x1[j] += sb * pv[4 + j]; s += x0[j] * x0[j] + x1[j] * x1[j]; }
;                     if (xb) store8bf(xb + off, x0, x1);
;                     else { *(f32x4*)(X + off) = x0; *(f32x4*)(X + off + 4) = x1; } }
.LBB0_164:
	global_store_dwordx4 v[204:205], v[140:143], off offset:512 nt
	global_store_dwordx4 v[204:205], v[160:163], off offset:528 nt
	s_cbranch_execnz .LBB0_163

;     __device__ __forceinline__ void operator()(const f32x4 (&acc)[2][2][4][2], const Unit& u, int wr, int wc, int fr, int fq, const LAS float* rsl) const {
;     ...
;             for (int m = 0; m < 4; ++m) { const int row = row0 + ai * 128 + m * 16; float s = 0.f; const int bt = ai * 4 + m;
;                 if (bt < 7) { const int nrow = row0 + ((bt + 1) >> 2) * 128 + ((bt + 1) & 3) * 16;
; #pragma unroll
;                     for (int bj = 0; bj < 2; ++bj) { const size_t off = (size_t)nrow * 1024 + col0 + bj * 128; xr[(bt + 1) & 1][bj] = *(const u32x4*)(x1b + off); pr[(bt + 1) & 1][bj] = *(const u32x4*)(pp + off); } }
; #pragma unroll
;                 for (int bj = 0; bj < 2; ++bj) { const size_t off = (size_t)row * 1024 + col0 + bj * 128;
;                     float xv[8], pv[8]; unpack8(xr[bt & 1][bj], xv); unpack8(pr[bt & 1][bj], pv);
;                     f32x4 x0 = (f32x4){xv[0], xv[1], xv[2], xv[3]}, x1 = (f32x4){xv[4], xv[5], xv[6], xv[7]};
;                     const f32x4 g0 = acc[ai][bj][m][0], g1 = acc[ai][bj][m][1];
; #pragma unroll
;                     for (int j = 0; j < 4; ++j) { float sa, sb; sigmoid2(g0[j], g1[j], sa, sb); x0[j] += sa * pv[j]; x1[j] += sb * pv[4 + j]; s += x0[j] * x0[j] + x1[j] * x1[j]; }
;                     if (xb) store8bf(xb + off, x0, x1);
;                     else { *(f32x4*)(X + off) = x0; *(f32x4*)(X + off + 4) = x1; } }
.LBB0_169:
	v_or_b32_e32 v128, 16, v194
	s_waitcnt lgkmcnt(0)
	v_ashrrev_i32_e32 v129, 31, v128
	v_lshlrev_b64 v[128:129], 10, v[128:129]
	v_lshl_add_u64 v[128:129], v[128:129], 0, v[190:191]
	v_lshlrev_b64 v[128:129], 1, v[128:129]
	v_lshl_add_u64 v[130:131], s[98:99], 0, v[128:129]
	global_load_dwordx4 v[152:155], v[130:131], off
	v_lshl_add_u64 v[130:131], s[64:65], 0, v[128:129]
	v_or_b32_e32 v128, 0x100, v128
	global_load_dwordx4 v[156:159], v[130:131], off
	v_lshl_add_u64 v[130:131], s[98:99], 0, v[128:129]
	v_lshl_add_u64 v[128:129], s[64:65], 0, v[128:129]
	global_load_dwordx4 v[136:139], v[130:131], off
	global_load_dwordx4 v[140:143], v[128:129], off
	v_max_f32_e64 v129, -v56, -v56
	v_min_f32_e32 v129, 0x42200000, v129
	v_mul_f32_e32 v129, 0x3fb8aa3b, v129
	v_max_f32_e64 v128, -v60, -v60
	v_exp_f32_e32 v130, v129
	v_max_f32_e64 v129, -v61, -v61
	v_max_f32_e64 v131, -v57, -v57
	v_min_f32_e32 v128, 0x42200000, v128
	v_min_f32_e32 v129, 0x42200000, v129
	v_min_f32_e32 v131, 0x42200000, v131
	v_mul_f32_e32 v128, 0x3fb8aa3b, v128
	v_mul_f32_e32 v129, 0x3fb8aa3b, v129
	v_mul_f32_e32 v131, 0x3fb8aa3b, v131
	v_exp_f32_e32 v128, v128
	v_exp_f32_e32 v129, v129
	v_exp_f32_e32 v131, v131
	s_waitcnt vmcnt(7)
	v_lshlrev_b32_e32 v160, 16, v148
	v_and_b32_e32 v161, 0xffff0000, v148
	v_pk_add_f32 v[204:205], v[128:129], 1.0 op_sel_hi:[1,0]
	v_pk_add_f32 v[130:131], v[130:131], 1.0 op_sel_hi:[1,0]
	s_waitcnt vmcnt(6)
	v_lshlrev_b32_e32 v162, 16, v164
	v_pk_mul_f32 v[128:129], v[204:205], v[130:131]
	v_and_b32_e32 v163, 0xffff0000, v164
	v_rcp_f32_e32 v206, v128
	v_rcp_f32_e32 v207, v129
	v_lshlrev_b32_e32 v196, 16, v150
	v_and_b32_e32 v197, 0xffff0000, v150
	v_lshlrev_b32_e32 v198, 16, v166
	v_and_b32_e32 v199, 0xffff0000, v166
	v_pk_mul_f32 v[128:129], v[130:131], v[206:207]
	v_pk_mul_f32 v[130:131], v[204:205], v[206:207]
	v_pk_fma_f32 v[128:129], v[128:129], v[162:163], v[160:161]
	v_pk_fma_f32 v[160:161], v[130:131], v[198:199], v[196:197]
	v_max_f32_e64 v131, -v58, -v58
	v_min_f32_e32 v131, 0x42200000, v131
	v_mul_f32_e32 v131, 0x3fb8aa3b, v131
	v_max_f32_e64 v130, -v62, -v62
	v_exp_f32_e32 v162, v131
	v_max_f32_e64 v131, -v63, -v63
	v_max_f32_e64 v148, -v59, -v59
	v_min_f32_e32 v130, 0x42200000, v130
	v_min_f32_e32 v131, 0x42200000, v131
	v_min_f32_e32 v148, 0x42200000, v148
	v_mul_f32_e32 v130, 0x3fb8aa3b, v130
	v_mul_f32_e32 v131, 0x3fb8aa3b, v131
	v_mul_f32_e32 v148, 0x3fb8aa3b, v148
	v_exp_f32_e32 v130, v130
	v_exp_f32_e32 v131, v131
	v_exp_f32_e32 v163, v148
	v_lshlrev_b32_e32 v148, 16, v149
	v_and_b32_e32 v149, 0xffff0000, v149
	v_pk_add_f32 v[196:197], v[130:131], 1.0 op_sel_hi:[1,0]
	v_pk_add_f32 v[162:163], v[162:163], 1.0 op_sel_hi:[1,0]
	v_lshlrev_b32_e32 v164, 16, v165
	v_pk_mul_f32 v[130:131], v[196:197], v[162:163]
	v_and_b32_e32 v165, 0xffff0000, v165
	v_rcp_f32_e32 v198, v130
	v_rcp_f32_e32 v199, v131
	v_lshlrev_b32_e32 v150, 16, v151
	v_and_b32_e32 v151, 0xffff0000, v151
	v_lshlrev_b32_e32 v166, 16, v167
	v_pk_mul_f32 v[130:131], v[162:163], v[198:199]
	v_and_b32_e32 v167, 0xffff0000, v167
	v_pk_fma_f32 v[130:131], v[130:131], v[164:165], v[148:149]
	v_pk_mul_f32 v[148:149], v[196:197], v[198:199]
	s_mov_b64 s[36:37], -1
	v_pk_fma_f32 v[162:163], v[148:149], v[166:167], v[150:151]
	s_and_b64 vcc, exec, s[96:97]
	v_lshl_add_u64 v[196:197], v[202:203], 2, s[8:9]
	s_cbranch_vccz .LBB0_171
	global_store_dwordx4 v[196:197], v[128:131], off nt
	global_store_dwordx4 v[196:197], v[160:163], off offset:16 nt
	s_mov_b64 s[36:37], 0

;     __device__ __forceinline__ void operator()(const f32x4 (&acc)[2][2][4][2], const Unit& u, int wr, int wc, int fr, int fq, const LAS float* rsl) const {
;     ...
;                     for (int j = 0; j < 4; ++j) { float sa, sb; sigmoid2(g0[j], g1[j], sa, sb); x0[j] += sa * pv[j]; x1[j] += sb * pv[4 + j]; s += x0[j] * x0[j] + x1[j] * x1[j]; }
;                     if (xb) store8bf(xb + off, x0, x1);
;                     else { *(f32x4*)(X + off) = x0; *(f32x4*)(X + off + 4) = x1; } }
.LBB0_176:
	global_store_dwordx4 v[196:197], v[148:151], off offset:512 nt
	global_store_dwordx4 v[196:197], v[164:167], off offset:528 nt
	s_cbranch_execnz .LBB0_175

;     __device__ __forceinline__ void operator()(const f32x4 (&acc)[2][2][4][2], const Unit& u, int wr, int wc, int fr, int fq, const LAS float* rsl) const {
;     ...
;             for (int m = 0; m < 4; ++m) { const int row = row0 + ai * 128 + m * 16; float s = 0.f; const int bt = ai * 4 + m;
;                 if (bt < 7) { const int nrow = row0 + ((bt + 1) >> 2) * 128 + ((bt + 1) & 3) * 16;
; #pragma unroll
;                     for (int bj = 0; bj < 2; ++bj) { const size_t off = (size_t)nrow * 1024 + col0 + bj * 128; xr[(bt + 1) & 1][bj] = *(const u32x4*)(x1b + off); pr[(bt + 1) & 1][bj] = *(const u32x4*)(pp + off); } }
; #pragma unroll
;                 for (int bj = 0; bj < 2; ++bj) { const size_t off = (size_t)row * 1024 + col0 + bj * 128;
;                     float xv[8], pv[8]; unpack8(xr[bt & 1][bj], xv); unpack8(pr[bt & 1][bj], pv);
;                     f32x4 x0 = (f32x4){xv[0], xv[1], xv[2], xv[3]}, x1 = (f32x4){xv[4], xv[5], xv[6], xv[7]};
;                     const f32x4 g0 = acc[ai][bj][m][0], g1 = acc[ai][bj][m][1];
; #pragma unroll
;                     for (int j = 0; j < 4; ++j) { float sa, sb; sigmoid2(g0[j], g1[j], sa, sb); x0[j] += sa * pv[j]; x1[j] += sb * pv[4 + j]; s += x0[j] * x0[j] + x1[j] * x1[j]; }
;                     if (xb) store8bf(xb + off, x0, x1);
;                     else { *(f32x4*)(X + off) = x0; *(f32x4*)(X + off + 4) = x1; } }
.LBB0_181:
	v_or_b32_e32 v128, 32, v194
	s_waitcnt lgkmcnt(0)
	v_ashrrev_i32_e32 v129, 31, v128
	v_lshlrev_b64 v[128:129], 10, v[128:129]
	v_lshl_add_u64 v[128:129], v[128:129], 0, v[190:191]
	v_lshlrev_b64 v[132:133], 1, v[128:129]
	v_lshl_add_u64 v[128:129], s[98:99], 0, v[132:133]
	global_load_dwordx4 v[144:147], v[128:129], off
	v_lshl_add_u64 v[128:129], s[64:65], 0, v[132:133]
	v_or_b32_e32 v132, 0x100, v132
	global_load_dwordx4 v[148:151], v[128:129], off
	v_lshl_add_u64 v[128:129], s[98:99], 0, v[132:133]
	v_lshl_add_u64 v[132:133], s[64:65], 0, v[132:133]
	global_load_dwordx4 v[128:131], v[128:129], off
	v_add_u32_e32 v196, 0x90, v192
	global_load_dwordx4 v[132:135], v[132:133], off
	v_ashrrev_i32_e32 v197, 31, v196
	v_lshlrev_b64 v[160:161], 10, v[196:197]
	v_lshl_add_u64 v[198:199], v[160:161], 0, v[190:191]
	v_max_f32_e64 v161, -v44, -v44
	v_min_f32_e32 v161, 0x42200000, v161
	v_mul_f32_e32 v161, 0x3fb8aa3b, v161
	v_max_f32_e64 v160, -v52, -v52
	v_exp_f32_e32 v162, v161
	v_max_f32_e64 v161, -v53, -v53
	v_max_f32_e64 v163, -v45, -v45
	v_min_f32_e32 v160, 0x42200000, v160
	v_min_f32_e32 v161, 0x42200000, v161
	v_min_f32_e32 v163, 0x42200000, v163
	v_mul_f32_e32 v160, 0x3fb8aa3b, v160
	v_mul_f32_e32 v161, 0x3fb8aa3b, v161
	v_mul_f32_e32 v163, 0x3fb8aa3b, v163
	v_exp_f32_e32 v160, v160
	v_exp_f32_e32 v161, v161
	v_exp_f32_e32 v163, v163
	s_waitcnt vmcnt(7)
	v_lshlrev_b32_e32 v164, 16, v152
	v_and_b32_e32 v165, 0xffff0000, v152
	v_pk_add_f32 v[204:205], v[160:161], 1.0 op_sel_hi:[1,0]
	v_pk_add_f32 v[162:163], v[162:163], 1.0 op_sel_hi:[1,0]
	v_max_f32_e64 v152, -v54, -v54
	v_pk_mul_f32 v[160:161], v[204:205], v[162:163]
	v_min_f32_e32 v152, 0x42200000, v152
	v_rcp_f32_e32 v206, v160
	v_rcp_f32_e32 v207, v161
	s_waitcnt vmcnt(6)
	v_lshlrev_b32_e32 v166, 16, v156
	v_and_b32_e32 v167, 0xffff0000, v156
	v_lshlrev_b32_e32 v200, 16, v154
	v_and_b32_e32 v201, 0xffff0000, v154
	v_lshlrev_b32_e32 v202, 16, v158
	v_and_b32_e32 v203, 0xffff0000, v158
	v_pk_mul_f32 v[160:161], v[162:163], v[206:207]
	v_pk_mul_f32 v[162:163], v[204:205], v[206:207]
	v_mul_f32_e32 v152, 0x3fb8aa3b, v152
	v_pk_fma_f32 v[160:161], v[160:161], v[166:167], v[164:165]
	v_pk_fma_f32 v[164:165], v[162:163], v[202:203], v[200:201]
	v_exp_f32_e32 v162, v152
	v_max_f32_e64 v152, -v46, -v46
	v_min_f32_e32 v152, 0x42200000, v152
	v_mul_f32_e32 v152, 0x3fb8aa3b, v152
	v_exp_f32_e32 v166, v152
	v_max_f32_e64 v152, -v55, -v55
	v_min_f32_e32 v152, 0x42200000, v152
	v_mul_f32_e32 v152, 0x3fb8aa3b, v152
	v_exp_f32_e32 v163, v152
	v_max_f32_e64 v152, -v47, -v47
	v_min_f32_e32 v152, 0x42200000, v152
	v_mul_f32_e32 v152, 0x3fb8aa3b, v152
	v_exp_f32_e32 v167, v152
	v_pk_add_f32 v[200:201], v[162:163], 1.0 op_sel_hi:[1,0]
	v_lshlrev_b32_e32 v152, 16, v153
	v_and_b32_e32 v153, 0xffff0000, v153
	v_pk_add_f32 v[166:167], v[166:167], 1.0 op_sel_hi:[1,0]
	v_lshlrev_b32_e32 v156, 16, v157
	v_pk_mul_f32 v[162:163], v[200:201], v[166:167]
	v_and_b32_e32 v157, 0xffff0000, v157
	v_rcp_f32_e32 v202, v162
	v_rcp_f32_e32 v203, v163
	v_lshlrev_b32_e32 v154, 16, v155
	v_and_b32_e32 v155, 0xffff0000, v155
	v_lshlrev_b32_e32 v158, 16, v159
	v_pk_mul_f32 v[162:163], v[166:167], v[202:203]
	v_and_b32_e32 v159, 0xffff0000, v159
	v_pk_fma_f32 v[162:163], v[162:163], v[156:157], v[152:153]
	v_pk_mul_f32 v[152:153], v[200:201], v[202:203]
	s_mov_b64 s[36:37], -1
	v_pk_fma_f32 v[166:167], v[152:153], v[158:159], v[154:155]
	s_and_b64 vcc, exec, s[96:97]
	v_lshl_add_u64 v[200:201], v[198:199], 2, s[8:9]
	s_cbranch_vccz .LBB0_183
	global_store_dwordx4 v[200:201], v[160:163], off nt
	global_store_dwordx4 v[200:201], v[164:167], off offset:16 nt
	s_mov_b64 s[36:37], 0

;     __device__ __forceinline__ void operator()(const f32x4 (&acc)[2][2][4][2], const Unit& u, int wr, int wc, int fr, int fq, const LAS float* rsl) const {
;     ...
;                     for (int j = 0; j < 4; ++j) { float sa, sb; sigmoid2(g0[j], g1[j], sa, sb); x0[j] += sa * pv[j]; x1[j] += sb * pv[4 + j]; s += x0[j] * x0[j] + x1[j] * x1[j]; }
;                     if (xb) store8bf(xb + off, x0, x1);
;                     else { *(f32x4*)(X + off) = x0; *(f32x4*)(X + off + 4) = x1; } }
.LBB0_188:
	global_store_dwordx4 v[200:201], v[152:155], off offset:512 nt
	global_store_dwordx4 v[200:201], v[156:159], off offset:528 nt
	s_cbranch_execnz .LBB0_187

;     __device__ __forceinline__ void operator()(const f32x4 (&acc)[2][2][4][2], const Unit& u, int wr, int wc, int fr, int fq, const LAS float* rsl) const {
;     ...
;             for (int m = 0; m < 4; ++m) { const int row = row0 + ai * 128 + m * 16; float s = 0.f; const int bt = ai * 4 + m;
;                 if (bt < 7) { const int nrow = row0 + ((bt + 1) >> 2) * 128 + ((bt + 1) & 3) * 16;
; #pragma unroll
;                     for (int bj = 0; bj < 2; ++bj) { const size_t off = (size_t)nrow * 1024 + col0 + bj * 128; xr[(bt + 1) & 1][bj] = *(const u32x4*)(x1b + off); pr[(bt + 1) & 1][bj] = *(const u32x4*)(pp + off); } }
; #pragma unroll
;                 for (int bj = 0; bj < 2; ++bj) { const size_t off = (size_t)row * 1024 + col0 + bj * 128;
;                     float xv[8], pv[8]; unpack8(xr[bt & 1][bj], xv); unpack8(pr[bt & 1][bj], pv);
;                     f32x4 x0 = (f32x4){xv[0], xv[1], xv[2], xv[3]}, x1 = (f32x4){xv[4], xv[5], xv[6], xv[7]};
;                     const f32x4 g0 = acc[ai][bj][m][0], g1 = acc[ai][bj][m][1];
; #pragma unroll
;                     for (int j = 0; j < 4; ++j) { float sa, sb; sigmoid2(g0[j], g1[j], sa, sb); x0[j] += sa * pv[j]; x1[j] += sb * pv[4 + j]; s += x0[j] * x0[j] + x1[j] * x1[j]; }
;                     if (xb) store8bf(xb + off, x0, x1);
;                     else { *(f32x4*)(X + off) = x0; *(f32x4*)(X + off + 4) = x1; } }
.LBB0_193:
	v_or_b32_e32 v136, 48, v194
	s_waitcnt lgkmcnt(0)
	v_ashrrev_i32_e32 v137, 31, v136
	v_lshlrev_b64 v[136:137], 10, v[136:137]
	v_lshl_add_u64 v[136:137], v[136:137], 0, v[190:191]
	v_lshlrev_b64 v[140:141], 1, v[136:137]
	v_lshl_add_u64 v[136:137], s[98:99], 0, v[140:141]
	global_load_dwordx4 v[152:155], v[136:137], off
	v_lshl_add_u64 v[136:137], s[64:65], 0, v[140:141]
	v_or_b32_e32 v140, 0x100, v140
	global_load_dwordx4 v[156:159], v[136:137], off
	v_lshl_add_u64 v[136:137], s[98:99], 0, v[140:141]
	v_lshl_add_u64 v[140:141], s[64:65], 0, v[140:141]
	global_load_dwordx4 v[136:139], v[136:137], off
	v_add_u32_e32 v196, 0xa0, v192
	global_load_dwordx4 v[140:143], v[140:141], off
	v_ashrrev_i32_e32 v197, 31, v196
	v_lshlrev_b64 v[160:161], 10, v[196:197]
	v_lshl_add_u64 v[194:195], v[160:161], 0, v[190:191]
	v_max_f32_e64 v161, -v28, -v28
	v_min_f32_e32 v161, 0x42200000, v161
	v_mul_f32_e32 v161, 0x3fb8aa3b, v161
	v_max_f32_e64 v160, -v36, -v36
	v_exp_f32_e32 v162, v161
	v_max_f32_e64 v161, -v37, -v37
	v_max_f32_e64 v163, -v29, -v29
	v_min_f32_e32 v160, 0x42200000, v160
	v_min_f32_e32 v161, 0x42200000, v161
	v_min_f32_e32 v163, 0x42200000, v163
	v_mul_f32_e32 v160, 0x3fb8aa3b, v160
	v_mul_f32_e32 v161, 0x3fb8aa3b, v161
	v_mul_f32_e32 v163, 0x3fb8aa3b, v163
	v_exp_f32_e32 v160, v160
	v_exp_f32_e32 v161, v161
	v_exp_f32_e32 v163, v163
	s_waitcnt vmcnt(7)
	v_lshlrev_b32_e32 v164, 16, v144
	v_and_b32_e32 v165, 0xffff0000, v144
	v_pk_add_f32 v[202:203], v[160:161], 1.0 op_sel_hi:[1,0]
	v_pk_add_f32 v[162:163], v[162:163], 1.0 op_sel_hi:[1,0]
	v_max_f32_e64 v144, -v38, -v38
	v_pk_mul_f32 v[160:161], v[202:203], v[162:163]
	v_min_f32_e32 v144, 0x42200000, v144
	v_rcp_f32_e32 v204, v160
	v_rcp_f32_e32 v205, v161
	s_waitcnt vmcnt(6)
	v_lshlrev_b32_e32 v166, 16, v148
	v_and_b32_e32 v167, 0xffff0000, v148
	v_lshlrev_b32_e32 v198, 16, v146
	v_and_b32_e32 v199, 0xffff0000, v146
	v_lshlrev_b32_e32 v200, 16, v150
	v_and_b32_e32 v201, 0xffff0000, v150
	v_pk_mul_f32 v[160:161], v[162:163], v[204:205]
	v_pk_mul_f32 v[162:163], v[202:203], v[204:205]
	v_mul_f32_e32 v144, 0x3fb8aa3b, v144
	v_pk_fma_f32 v[160:161], v[160:161], v[166:167], v[164:165]
	v_pk_fma_f32 v[164:165], v[162:163], v[200:201], v[198:199]
	v_exp_f32_e32 v162, v144
	v_max_f32_e64 v144, -v30, -v30
	v_min_f32_e32 v144, 0x42200000, v144
	v_mul_f32_e32 v144, 0x3fb8aa3b, v144
	v_exp_f32_e32 v166, v144
	v_max_f32_e64 v144, -v39, -v39
	v_min_f32_e32 v144, 0x42200000, v144
	v_mul_f32_e32 v144, 0x3fb8aa3b, v144
	v_exp_f32_e32 v163, v144
	v_max_f32_e64 v144, -v31, -v31
	v_min_f32_e32 v144, 0x42200000, v144
	v_mul_f32_e32 v144, 0x3fb8aa3b, v144
	v_exp_f32_e32 v167, v144
	v_pk_add_f32 v[198:199], v[162:163], 1.0 op_sel_hi:[1,0]
	v_lshlrev_b32_e32 v144, 16, v145
	v_and_b32_e32 v145, 0xffff0000, v145
	v_pk_add_f32 v[166:167], v[166:167], 1.0 op_sel_hi:[1,0]
	v_lshlrev_b32_e32 v148, 16, v149
	v_pk_mul_f32 v[162:163], v[198:199], v[166:167]
	v_and_b32_e32 v149, 0xffff0000, v149
	v_rcp_f32_e32 v200, v162
	v_rcp_f32_e32 v201, v163
	v_lshlrev_b32_e32 v146, 16, v147
	v_and_b32_e32 v147, 0xffff0000, v147
	v_lshlrev_b32_e32 v150, 16, v151
	v_pk_mul_f32 v[162:163], v[166:167], v[200:201]
	v_and_b32_e32 v151, 0xffff0000, v151
	v_pk_fma_f32 v[162:163], v[162:163], v[148:149], v[144:145]
	v_pk_mul_f32 v[144:145], v[198:199], v[200:201]
	s_mov_b64 s[36:37], -1
	v_pk_fma_f32 v[166:167], v[144:145], v[150:151], v[146:147]
	s_and_b64 vcc, exec, s[96:97]
	v_lshl_add_u64 v[198:199], v[194:195], 2, s[8:9]
	s_cbranch_vccz .LBB0_195
	global_store_dwordx4 v[198:199], v[160:163], off nt
	global_store_dwordx4 v[198:199], v[164:167], off offset:16 nt
	s_mov_b64 s[36:37], 0

;     __device__ __forceinline__ void operator()(const f32x4 (&acc)[2][2][4][2], const Unit& u, int wr, int wc, int fr, int fq, const LAS float* rsl) const {
;     ...
;                     for (int j = 0; j < 4; ++j) { float sa, sb; sigmoid2(g0[j], g1[j], sa, sb); x0[j] += sa * pv[j]; x1[j] += sb * pv[4 + j]; s += x0[j] * x0[j] + x1[j] * x1[j]; }
;                     if (xb) store8bf(xb + off, x0, x1);
;                     else { *(f32x4*)(X + off) = x0; *(f32x4*)(X + off + 4) = x1; } }
.LBB0_200:
	global_store_dwordx4 v[198:199], v[144:147], off offset:512 nt
	global_store_dwordx4 v[198:199], v[148:151], off offset:528 nt
	s_cbranch_execnz .LBB0_199

;     __device__ __forceinline__ void operator()(const f32x4 (&acc)[2][2][4][2], const Unit& u, int wr, int wc, int fr, int fq, const LAS float* rsl) const {
;     ...
;             for (int m = 0; m < 4; ++m) { const int row = row0 + ai * 128 + m * 16; float s = 0.f; const int bt = ai * 4 + m;
;                 if (bt < 7) { const int nrow = row0 + ((bt + 1) >> 2) * 128 + ((bt + 1) & 3) * 16;
; #pragma unroll
;                     for (int bj = 0; bj < 2; ++bj) { const size_t off = (size_t)nrow * 1024 + col0 + bj * 128; xr[(bt + 1) & 1][bj] = *(const u32x4*)(x1b + off); pr[(bt + 1) & 1][bj] = *(const u32x4*)(pp + off); } }
; #pragma unroll
;                 for (int bj = 0; bj < 2; ++bj) { const size_t off = (size_t)row * 1024 + col0 + bj * 128;
;                     float xv[8], pv[8]; unpack8(xr[bt & 1][bj], xv); unpack8(pr[bt & 1][bj], pv);
;                     f32x4 x0 = (f32x4){xv[0], xv[1], xv[2], xv[3]}, x1 = (f32x4){xv[4], xv[5], xv[6], xv[7]};
;                     const f32x4 g0 = acc[ai][bj][m][0], g1 = acc[ai][bj][m][1];
; #pragma unroll
;                     for (int j = 0; j < 4; ++j) { float sa, sb; sigmoid2(g0[j], g1[j], sa, sb); x0[j] += sa * pv[j]; x1[j] += sb * pv[4 + j]; s += x0[j] * x0[j] + x1[j] * x1[j]; }
;                     if (xb) store8bf(xb + off, x0, x1);
;                     else { *(f32x4*)(X + off) = x0; *(f32x4*)(X + off + 4) = x1; } }
.LBB0_205:
	v_add_u32_e32 v160, 0xb0, v192
	v_ashrrev_i32_e32 v161, 31, v160
	s_waitcnt lgkmcnt(0)
	v_lshlrev_b64 v[128:129], 10, v[160:161]
	v_lshl_add_u64 v[162:163], v[128:129], 0, v[190:191]
	v_max_f32_e64 v129, -v12, -v12
	v_min_f32_e32 v129, 0x42200000, v129
	v_mul_f32_e32 v129, 0x3fb8aa3b, v129
	v_max_f32_e64 v128, -v20, -v20
	v_exp_f32_e32 v130, v129
	v_max_f32_e64 v129, -v21, -v21
	v_max_f32_e64 v131, -v13, -v13
	v_min_f32_e32 v128, 0x42200000, v128
	v_min_f32_e32 v129, 0x42200000, v129
	v_min_f32_e32 v131, 0x42200000, v131
	v_mul_f32_e32 v128, 0x3fb8aa3b, v128
	v_mul_f32_e32 v129, 0x3fb8aa3b, v129
	v_mul_f32_e32 v131, 0x3fb8aa3b, v131
	v_exp_f32_e32 v128, v128
	v_exp_f32_e32 v129, v129
	v_exp_f32_e32 v131, v131
	s_waitcnt vmcnt(3)
	v_lshlrev_b32_e32 v132, 16, v152
	v_and_b32_e32 v133, 0xffff0000, v152
	v_pk_add_f32 v[148:149], v[128:129], 1.0 op_sel_hi:[1,0]
	v_pk_add_f32 v[130:131], v[130:131], 1.0 op_sel_hi:[1,0]
	s_waitcnt vmcnt(2)
	v_lshlrev_b32_e32 v134, 16, v156
	v_pk_mul_f32 v[128:129], v[148:149], v[130:131]
	v_and_b32_e32 v135, 0xffff0000, v156
	v_rcp_f32_e32 v150, v128
	v_rcp_f32_e32 v151, v129
	v_lshlrev_b32_e32 v144, 16, v154
	v_and_b32_e32 v145, 0xffff0000, v154
	v_lshlrev_b32_e32 v146, 16, v158
	v_and_b32_e32 v147, 0xffff0000, v158
	v_pk_mul_f32 v[128:129], v[130:131], v[150:151]
	v_pk_mul_f32 v[130:131], v[148:149], v[150:151]
	v_pk_fma_f32 v[128:129], v[128:129], v[134:135], v[132:133]
	v_pk_fma_f32 v[132:133], v[130:131], v[146:147], v[144:145]
	v_max_f32_e64 v131, -v14, -v14
	v_min_f32_e32 v131, 0x42200000, v131
	v_mul_f32_e32 v131, 0x3fb8aa3b, v131
	v_max_f32_e64 v130, -v22, -v22
	v_exp_f32_e32 v134, v131
	v_max_f32_e64 v131, -v23, -v23
	v_max_f32_e64 v135, -v15, -v15
	v_min_f32_e32 v130, 0x42200000, v130
	v_min_f32_e32 v131, 0x42200000, v131
	v_min_f32_e32 v135, 0x42200000, v135
	v_mul_f32_e32 v130, 0x3fb8aa3b, v130
	v_mul_f32_e32 v131, 0x3fb8aa3b, v131
	v_mul_f32_e32 v135, 0x3fb8aa3b, v135
	v_exp_f32_e32 v130, v130
	v_exp_f32_e32 v131, v131
	v_exp_f32_e32 v135, v135
	v_lshlrev_b32_e32 v144, 16, v153
	v_and_b32_e32 v145, 0xffff0000, v153
	v_pk_add_f32 v[152:153], v[130:131], 1.0 op_sel_hi:[1,0]
	v_pk_add_f32 v[134:135], v[134:135], 1.0 op_sel_hi:[1,0]
	v_lshlrev_b32_e32 v148, 16, v155
	v_pk_mul_f32 v[130:131], v[152:153], v[134:135]
	v_and_b32_e32 v149, 0xffff0000, v155
	v_rcp_f32_e32 v154, v130
	v_rcp_f32_e32 v155, v131
	v_lshlrev_b32_e32 v146, 16, v157
	v_and_b32_e32 v147, 0xffff0000, v157
	v_lshlrev_b32_e32 v150, 16, v159
	v_and_b32_e32 v151, 0xffff0000, v159
	v_pk_mul_f32 v[130:131], v[134:135], v[154:155]
	v_pk_mul_f32 v[134:135], v[152:153], v[154:155]
	v_pk_fma_f32 v[130:131], v[130:131], v[146:147], v[144:145]
	v_pk_fma_f32 v[134:135], v[134:135], v[150:151], v[148:149]
	s_mov_b64 s[36:37], -1
	s_and_b64 vcc, exec, s[96:97]
	v_lshl_add_u64 v[152:153], v[162:163], 2, s[8:9]
	s_cbranch_vccz .LBB0_207
	global_store_dwordx4 v[152:153], v[128:131], off nt
	global_store_dwordx4 v[152:153], v[132:135], off offset:16 nt
	s_mov_b64 s[36:37], 0

;     __device__ __forceinline__ void operator()(const f32x4 (&acc)[2][2][4][2], const Unit& u, int wr, int wc, int fr, int fq, const LAS float* rsl) const {
;     ...
;                     for (int j = 0; j < 4; ++j) { float sa, sb; sigmoid2(g0[j], g1[j], sa, sb); x0[j] += sa * pv[j]; x1[j] += sb * pv[4 + j]; s += x0[j] * x0[j] + x1[j] * x1[j]; }
;                     if (xb) store8bf(xb + off, x0, x1);
;                     else { *(f32x4*)(X + off) = x0; *(f32x4*)(X + off + 4) = x1; } }
.LBB0_212:
	global_store_dwordx4 v[152:153], v[144:147], off offset:512 nt
	global_store_dwordx4 v[152:153], v[148:151], off offset:528 nt
	s_cbranch_execnz .LBB0_211
